# mixer part P: both per-column bias loads of the final stage issued at the part head (kept in flight through the stage-in wait)
# speedup vs baseline: 1.0010x; 1.0010x over previous
.LBB0_610:
	s_or_b64 exec, exec, s[26:27]
	v_add_u32_e32 v21, s44, v20
	v_mov_b64_e32 v[34:35], s[6:7]
	v_mad_i64_i32 v[22:23], s[26:27], v21, s3, v[34:35]
	v_add_u32_e32 v26, 16, v21
	v_lshl_add_u64 v[22:23], v[22:23], 0, v[148:149]
	v_mad_i64_i32 v[26:27], s[26:27], v26, s3, v[34:35]
	v_add_u32_e32 v30, 32, v21
	global_load_dwordx4 v[22:25], v[22:23], off offset:2560 nt
	v_lshl_add_u64 v[26:27], v[26:27], 0, v[148:149]
	v_mad_i64_i32 v[30:31], s[26:27], v30, s3, v[34:35]
	v_add_u32_e32 v21, 48, v21
	global_load_dwordx4 v[26:29], v[26:27], off offset:2560 nt
	v_lshl_add_u64 v[30:31], v[30:31], 0, v[148:149]
	v_mad_i64_i32 v[34:35], s[26:27], v21, s3, v[34:35]
	global_load_dwordx4 v[30:33], v[30:31], off offset:2560 nt
	v_lshl_add_u64 v[34:35], v[34:35], 0, v[148:149]
	global_load_dwordx4 v[34:37], v[34:35], off offset:2560 nt
	v_lshlrev_b32_e32 v21, 4, v50
	v_and_b32_e32 v38, 0x1f0, v21
	v_and_b32_e32 v21, 0xfffffe00, v21
	v_readlane_b32 s23, v254, 38
	s_ashr_i32 s42, s45, 1
	s_andn2_b32 s42, s42, 63
	v_add3_u32 v21, s23, v38, v21
	s_movk_i32 s23, 0x210
	s_lshr_b32 s26, s45, 1
	s_waitcnt vmcnt(4)
	ds_write_b128 v21, v[4:7]
	ds_write_b128 v21, v[0:3] offset:8192
	ds_write_b128 v21, v[12:15] offset:16384
	ds_write_b128 v21, v[8:11] offset:24576
	ds_write_b128 v21, v[16:19] offset:32768
	v_mul_lo_u32 v0, v20, s23
	s_add_i32 s23, s42, s24
	s_and_b32 s43, s26, 32
	v_and_b32_e32 v49, 15, v50
	v_add3_u32 v0, 0, v38, v0
	s_or_b32 s23, s23, s43
	v_bfe_u32 v48, v50, 4, 2
	v_readlane_b32 s26, v254, 54
	v_lshlrev_b32_e32 v148, 4, v48
	v_readlane_b32 s27, v254, 55
	s_cmp_lg_u64 s[56:57], 0
	v_cmp_eq_u32_e32 vcc, 0, v50
	v_lshl_add_u64 v[2:3], s[26:27], 0, v[148:149]
	s_cselect_b64 s[26:27], -1, 0
	s_and_b64 s[48:49], s[26:27], vcc
	s_waitcnt vmcnt(3)
	ds_write_b128 v0, v[22:25] offset:33792
	s_waitcnt vmcnt(2)
	ds_write_b128 v0, v[26:29] offset:42240
	s_waitcnt vmcnt(1)
	ds_write_b128 v0, v[30:33] offset:50688
	s_waitcnt vmcnt(0)
	ds_write_b128 v0, v[34:37] offset:59136
	v_or_b32_e32 v0, s23, v49
	v_ashrrev_i32_e32 v1, 31, v0
	v_lshlrev_b64 v[4:5], 7, v[0:1]
	v_or_b32_e32 v0, 16, v0
	v_ashrrev_i32_e32 v1, 31, v0
	v_lshl_add_u64 v[4:5], v[2:3], 0, v[4:5]
	v_lshlrev_b64 v[0:1], 7, v[0:1]
	global_load_dwordx4 v[16:19], v[4:5], off
	global_load_dwordx4 v[20:23], v[4:5], off offset:64
	v_lshl_add_u64 v[4:5], v[2:3], 0, v[0:1]
	global_load_dwordx4 v[0:3], v[4:5], off
	s_nop 0
	global_load_dwordx4 v[4:7], v[4:5], off offset:64
	v_or_b32_e32 v250, s43, v49
	v_or_b32_e32 v250, s42, v250
	v_add_u32_e32 v250, s24, v250
	v_ashrrev_i32_e32 v251, 31, v250
	v_lshl_add_u64 v[250:251], v[250:251], 2, s[88:89]
	global_load_dword v57, v[250:251], off
	global_load_dword v249, v[250:251], off offset:64
	s_waitcnt vmcnt(6)
	s_waitcnt lgkmcnt(0)
	s_barrier
	s_and_saveexec_b64 s[26:27], s[48:49]
	s_cbranch_execz .LBB0_613
	global_atomic_add v149, v210, s[56:57]
	s_andn2_b64 vcc, exec, s[58:59]
	s_cbranch_vccnz .LBB0_613
	global_atomic_add v149, v210, s[56:57] offset:256
.LBB0_613:
	s_or_b64 exec, exec, s[26:27]
	v_bfe_u32 v32, v50, 3, 2
	v_ashrrev_i32_e32 v29, 3, v50
	v_lshlrev_b32_e64 v25, v32, 1
	v_and_b32_e32 v31, -4, v29
	v_and_b32_e32 v24, 31, v50
	v_sub_u32_e32 v8, v31, v25
	v_lshlrev_b32_e32 v8, 9, v8
	v_lshlrev_b32_e32 v28, 4, v24
	v_readlane_b32 s23, v254, 38
	v_cmp_lt_u32_e32 vcc, 7, v24
	s_nop 0
	v_add3_u32 v12, v8, s23, v28
	ds_read_b128 v[8:11], v12 offset:4096
	ds_read_b128 v[34:37], v12 offset:4608
	v_add_u32_e32 v30, 0x1000, v12
	v_cmp_lt_u32_e64 s[66:67], 7, v24
	v_cmp_lt_u32_e64 s[68:69], 15, v24
	v_cmp_eq_u32_e64 s[70:71], 3, v32
	s_mov_b64 s[72:73], exec
	s_movk_i32 s74, 0x200
	s_movk_i32 s75, 0x400
	v_lshl_add_u32 v96, s74, v32, v30
	v_lshl_add_u32 v97, s75, v32, v30
	v_or_b32_e32 v138, s43, v49
	v_or_b32_e32 v138, s42, v138
	v_lshlrev_b32_e32 v138, 1, v138
	v_mul_u32_u24_e32 v139, 0x840, v48
	v_add_u32_e32 v138, v138, v139
	s_mov_b64 exec, s[66:67]
	ds_read_b128 v[154:157], v30 offset:1024
	ds_read_b128 v[158:161], v30 offset:1536
	s_mov_b64 exec, s[68:69]
	ds_read_b128 v[162:165], v30 offset:2048
	ds_read_b128 v[166:169], v30 offset:2560
	ds_read_b128 v[170:173], v30 offset:3072
	ds_read_b128 v[174:177], v30 offset:3584
	s_mov_b64 exec, s[70:71]
	ds_read_b128 v[178:181], v30 offset:4096
	ds_read_b128 v[182:185], v30 offset:4608
	ds_read_b128 v[186:189], v30 offset:5120
	ds_read_b128 v[190:193], v30 offset:5632
	ds_read_b128 v[194:197], v30 offset:6144
	ds_read_b128 v[198:201], v30 offset:6656
	ds_read_b128 v[202:205], v30 offset:7168
	s_mov_b64 exec, s[72:73]
	s_waitcnt lgkmcnt(14)
	v_lshlrev_b32_e32 v12, 16, v8
	v_and_b32_e32 v13, 0xffff0000, v8
	v_lshlrev_b32_e32 v14, 16, v10
	v_and_b32_e32 v15, 0xffff0000, v10
	v_lshlrev_b32_e32 v10, 16, v11
	v_and_b32_e32 v11, 0xffff0000, v11
	v_pk_add_f32 v[12:13], v[12:13], 0 op_sel_hi:[1,0]
	v_lshlrev_b32_e32 v8, 16, v9
	v_and_b32_e32 v9, 0xffff0000, v9
	v_pk_add_f32 v[38:39], v[10:11], 0 op_sel_hi:[1,0]
	s_waitcnt lgkmcnt(13)
	v_lshlrev_b32_e32 v10, 16, v34
	v_and_b32_e32 v11, 0xffff0000, v34
	v_pk_add_f32 v[8:9], v[8:9], 0 op_sel_hi:[1,0]
	v_pk_add_f32 v[26:27], v[14:15], 0 op_sel_hi:[1,0]
	v_pk_add_f32 v[14:15], v[12:13], v[10:11]
	v_lshlrev_b32_e32 v10, 16, v35
	v_and_b32_e32 v11, 0xffff0000, v35
	v_pk_add_f32 v[12:13], v[8:9], v[10:11]
	v_lshlrev_b32_e32 v8, 16, v36
	v_and_b32_e32 v9, 0xffff0000, v36
	v_pk_add_f32 v[10:11], v[26:27], v[8:9]
	v_lshlrev_b32_e32 v8, 16, v37
	v_and_b32_e32 v9, 0xffff0000, v37
	v_pk_add_f32 v[8:9], v[38:39], v[8:9]
	s_mov_b64 exec, s[70:71]
	ds_read_b128 v[206:209], v30 offset:7680
	s_mov_b64 exec, s[72:73]
	ds_read_b128 v[98:101], v96
	s_mov_b64 exec, s[66:67]
	s_waitcnt lgkmcnt(14)
	v_lshlrev_b32_e32 v26, 16, v154
	v_and_b32_e32 v27, 0xffff0000, v154
	v_pk_add_f32 v[14:15], v[14:15], v[26:27]
	v_lshlrev_b32_e32 v26, 16, v155
	v_and_b32_e32 v27, 0xffff0000, v155
	v_pk_add_f32 v[12:13], v[12:13], v[26:27]
	v_lshlrev_b32_e32 v26, 16, v156
	v_and_b32_e32 v27, 0xffff0000, v156
	v_pk_add_f32 v[10:11], v[10:11], v[26:27]
	v_lshlrev_b32_e32 v26, 16, v157
	v_and_b32_e32 v27, 0xffff0000, v157
	v_pk_add_f32 v[8:9], v[8:9], v[26:27]
	s_waitcnt lgkmcnt(13)
	v_lshlrev_b32_e32 v26, 16, v158
	v_and_b32_e32 v27, 0xffff0000, v158
	v_pk_add_f32 v[14:15], v[14:15], v[26:27]
	v_lshlrev_b32_e32 v26, 16, v159
	v_and_b32_e32 v27, 0xffff0000, v159
	v_pk_add_f32 v[12:13], v[12:13], v[26:27]
	v_lshlrev_b32_e32 v26, 16, v160
	v_and_b32_e32 v27, 0xffff0000, v160
	v_pk_add_f32 v[10:11], v[10:11], v[26:27]
	v_lshlrev_b32_e32 v26, 16, v161
	v_and_b32_e32 v27, 0xffff0000, v161
	v_pk_add_f32 v[8:9], v[8:9], v[26:27]
	s_mov_b64 exec, s[72:73]
	ds_read_u16 v64, v138 offset:33792
	ds_read_u16 v65, v138 offset:34320
	s_mov_b64 exec, s[68:69]
	s_waitcnt lgkmcnt(14)
	v_lshlrev_b32_e32 v26, 16, v162
	v_and_b32_e32 v27, 0xffff0000, v162
	v_pk_add_f32 v[14:15], v[14:15], v[26:27]
	v_lshlrev_b32_e32 v26, 16, v163
	v_and_b32_e32 v27, 0xffff0000, v163
	v_pk_add_f32 v[12:13], v[12:13], v[26:27]
	v_lshlrev_b32_e32 v26, 16, v164
	v_and_b32_e32 v27, 0xffff0000, v164
	v_pk_add_f32 v[10:11], v[10:11], v[26:27]
	v_lshlrev_b32_e32 v26, 16, v165
	v_and_b32_e32 v27, 0xffff0000, v165
	v_pk_add_f32 v[8:9], v[8:9], v[26:27]
	s_waitcnt lgkmcnt(13)
	v_lshlrev_b32_e32 v26, 16, v166
	v_and_b32_e32 v27, 0xffff0000, v166
	v_pk_add_f32 v[14:15], v[14:15], v[26:27]
	v_lshlrev_b32_e32 v26, 16, v167
	v_and_b32_e32 v27, 0xffff0000, v167
	v_pk_add_f32 v[12:13], v[12:13], v[26:27]
	v_lshlrev_b32_e32 v26, 16, v168
	v_and_b32_e32 v27, 0xffff0000, v168
	v_pk_add_f32 v[10:11], v[10:11], v[26:27]
	v_lshlrev_b32_e32 v26, 16, v169
	v_and_b32_e32 v27, 0xffff0000, v169
	v_pk_add_f32 v[8:9], v[8:9], v[26:27]
	s_waitcnt lgkmcnt(12)
	v_lshlrev_b32_e32 v26, 16, v170
	v_and_b32_e32 v27, 0xffff0000, v170
	v_pk_add_f32 v[14:15], v[14:15], v[26:27]
	v_lshlrev_b32_e32 v26, 16, v171
	v_and_b32_e32 v27, 0xffff0000, v171
	v_pk_add_f32 v[12:13], v[12:13], v[26:27]
	v_lshlrev_b32_e32 v26, 16, v172
	v_and_b32_e32 v27, 0xffff0000, v172
	v_pk_add_f32 v[10:11], v[10:11], v[26:27]
	v_lshlrev_b32_e32 v26, 16, v173
	v_and_b32_e32 v27, 0xffff0000, v173
	v_pk_add_f32 v[8:9], v[8:9], v[26:27]
	s_waitcnt lgkmcnt(11)
	v_lshlrev_b32_e32 v26, 16, v174
	v_and_b32_e32 v27, 0xffff0000, v174
	v_pk_add_f32 v[14:15], v[14:15], v[26:27]
	v_lshlrev_b32_e32 v26, 16, v175
	v_and_b32_e32 v27, 0xffff0000, v175
	v_pk_add_f32 v[12:13], v[12:13], v[26:27]
	v_lshlrev_b32_e32 v26, 16, v176
	v_and_b32_e32 v27, 0xffff0000, v176
	v_pk_add_f32 v[10:11], v[10:11], v[26:27]
	v_lshlrev_b32_e32 v26, 16, v177
	v_and_b32_e32 v27, 0xffff0000, v177
	v_pk_add_f32 v[8:9], v[8:9], v[26:27]
	s_mov_b64 exec, s[72:73]
	ds_read_u16 v66, v138 offset:34848
	ds_read_b128 v[102:105], v30
	ds_read_u16 v67, v138 offset:42240
	ds_read_u16 v68, v138 offset:35376
	s_mov_b64 exec, s[70:71]
	s_waitcnt lgkmcnt(14)
	v_lshlrev_b32_e32 v26, 16, v178
	v_and_b32_e32 v27, 0xffff0000, v178
	v_pk_add_f32 v[14:15], v[14:15], v[26:27]
	v_lshlrev_b32_e32 v26, 16, v179
	v_and_b32_e32 v27, 0xffff0000, v179
	v_pk_add_f32 v[12:13], v[12:13], v[26:27]
	v_lshlrev_b32_e32 v26, 16, v180
	v_and_b32_e32 v27, 0xffff0000, v180
	v_pk_add_f32 v[10:11], v[10:11], v[26:27]
	v_lshlrev_b32_e32 v26, 16, v181
	v_and_b32_e32 v27, 0xffff0000, v181
	v_pk_add_f32 v[8:9], v[8:9], v[26:27]
	s_waitcnt lgkmcnt(13)
	v_lshlrev_b32_e32 v26, 16, v182
	v_and_b32_e32 v27, 0xffff0000, v182
	v_pk_add_f32 v[14:15], v[14:15], v[26:27]
	v_lshlrev_b32_e32 v26, 16, v183
	v_and_b32_e32 v27, 0xffff0000, v183
	v_pk_add_f32 v[12:13], v[12:13], v[26:27]
	v_lshlrev_b32_e32 v26, 16, v184
	v_and_b32_e32 v27, 0xffff0000, v184
	v_pk_add_f32 v[10:11], v[10:11], v[26:27]
	v_lshlrev_b32_e32 v26, 16, v185
	v_and_b32_e32 v27, 0xffff0000, v185
	v_pk_add_f32 v[8:9], v[8:9], v[26:27]
	s_waitcnt lgkmcnt(12)
	v_lshlrev_b32_e32 v26, 16, v186
	v_and_b32_e32 v27, 0xffff0000, v186
	v_pk_add_f32 v[14:15], v[14:15], v[26:27]
	v_lshlrev_b32_e32 v26, 16, v187
	v_and_b32_e32 v27, 0xffff0000, v187
	v_pk_add_f32 v[12:13], v[12:13], v[26:27]
	v_lshlrev_b32_e32 v26, 16, v188
	v_and_b32_e32 v27, 0xffff0000, v188
	v_pk_add_f32 v[10:11], v[10:11], v[26:27]
	v_lshlrev_b32_e32 v26, 16, v189
	v_and_b32_e32 v27, 0xffff0000, v189
	v_pk_add_f32 v[8:9], v[8:9], v[26:27]
	s_waitcnt lgkmcnt(11)
	v_lshlrev_b32_e32 v26, 16, v190
	v_and_b32_e32 v27, 0xffff0000, v190
	v_pk_add_f32 v[14:15], v[14:15], v[26:27]
	v_lshlrev_b32_e32 v26, 16, v191
	v_and_b32_e32 v27, 0xffff0000, v191
	v_pk_add_f32 v[12:13], v[12:13], v[26:27]
	v_lshlrev_b32_e32 v26, 16, v192
	v_and_b32_e32 v27, 0xffff0000, v192
	v_pk_add_f32 v[10:11], v[10:11], v[26:27]
	v_lshlrev_b32_e32 v26, 16, v193
	v_and_b32_e32 v27, 0xffff0000, v193
	v_pk_add_f32 v[8:9], v[8:9], v[26:27]
	s_waitcnt lgkmcnt(10)
	v_lshlrev_b32_e32 v26, 16, v194
	v_and_b32_e32 v27, 0xffff0000, v194
	v_pk_add_f32 v[14:15], v[14:15], v[26:27]
	v_lshlrev_b32_e32 v26, 16, v195
	v_and_b32_e32 v27, 0xffff0000, v195
	v_pk_add_f32 v[12:13], v[12:13], v[26:27]
	v_lshlrev_b32_e32 v26, 16, v196
	v_and_b32_e32 v27, 0xffff0000, v196
	v_pk_add_f32 v[10:11], v[10:11], v[26:27]
	v_lshlrev_b32_e32 v26, 16, v197
	v_and_b32_e32 v27, 0xffff0000, v197
	v_pk_add_f32 v[8:9], v[8:9], v[26:27]
	s_waitcnt lgkmcnt(9)
	v_lshlrev_b32_e32 v26, 16, v198
	v_and_b32_e32 v27, 0xffff0000, v198
	v_pk_add_f32 v[14:15], v[14:15], v[26:27]
	v_lshlrev_b32_e32 v26, 16, v199
	v_and_b32_e32 v27, 0xffff0000, v199
	v_pk_add_f32 v[12:13], v[12:13], v[26:27]
	v_lshlrev_b32_e32 v26, 16, v200
	v_and_b32_e32 v27, 0xffff0000, v200
	v_pk_add_f32 v[10:11], v[10:11], v[26:27]
	v_lshlrev_b32_e32 v26, 16, v201
	v_and_b32_e32 v27, 0xffff0000, v201
	v_pk_add_f32 v[8:9], v[8:9], v[26:27]
	s_waitcnt lgkmcnt(8)
	v_lshlrev_b32_e32 v26, 16, v202
	v_and_b32_e32 v27, 0xffff0000, v202
	v_pk_add_f32 v[14:15], v[14:15], v[26:27]
	v_lshlrev_b32_e32 v26, 16, v203
	v_and_b32_e32 v27, 0xffff0000, v203
	v_pk_add_f32 v[12:13], v[12:13], v[26:27]
	v_lshlrev_b32_e32 v26, 16, v204
	v_and_b32_e32 v27, 0xffff0000, v204
	v_pk_add_f32 v[10:11], v[10:11], v[26:27]
	v_lshlrev_b32_e32 v26, 16, v205
	v_and_b32_e32 v27, 0xffff0000, v205
	v_pk_add_f32 v[8:9], v[8:9], v[26:27]
	s_waitcnt lgkmcnt(7)
	v_lshlrev_b32_e32 v26, 16, v206
	v_and_b32_e32 v27, 0xffff0000, v206
	v_pk_add_f32 v[14:15], v[14:15], v[26:27]
	v_lshlrev_b32_e32 v26, 16, v207
	v_and_b32_e32 v27, 0xffff0000, v207
	v_pk_add_f32 v[12:13], v[12:13], v[26:27]
	v_lshlrev_b32_e32 v26, 16, v208
	v_and_b32_e32 v27, 0xffff0000, v208
	v_pk_add_f32 v[10:11], v[10:11], v[26:27]
	v_lshlrev_b32_e32 v26, 16, v209
	v_and_b32_e32 v27, 0xffff0000, v209
	v_pk_add_f32 v[8:9], v[8:9], v[26:27]
	s_mov_b64 exec, s[72:73]
	ds_read_u16 v69, v138 offset:42768
	ds_read_b128 v[106:109], v97
	ds_read_u16 v70, v138 offset:43296
	ds_read_u16 v71, v138 offset:50688
	ds_read_u16 v72, v138 offset:43824
	ds_read_b128 v[110:113], v96 offset:512
	ds_read_u16 v73, v138 offset:59136
	ds_read_u16 v74, v138 offset:33824
	v_add_u32_e32 v26, s47, v31
	v_sub_u32_e32 v27, v26, v25
	v_add_u32_e32 v26, v26, v25
	v_max_i32_e32 v27, 0, v27
	v_min_i32_e32 v26, s46, v26
	v_sub_u32_e32 v26, v26, v27
	v_cvt_f32_i32_e32 v26, v26
	v_lshlrev_b32_e32 v33, 9, v31
	v_readlane_b32 s49, v254, 38
	v_add_u32_e32 v24, 0, v28
	v_div_scale_f32 v27, s[26:27], v26, v26, 1.0
	v_add3_u32 v33, s49, v33, v28
	s_waitcnt lgkmcnt(14)
	v_mov_b32_e32 v34, v98
	v_mov_b32_e32 v35, v99
	v_mov_b32_e32 v36, v100
	v_mov_b32_e32 v37, v101
	v_rcp_f32_e32 v33, v27
	s_movk_i32 s48, 0x210
	s_movk_i32 s23, 0x400
	v_lshl_add_u32 v45, s23, v32, v30
	v_fma_f32 v38, -v27, v33, 1.0
	v_fmac_f32_e32 v33, v38, v33
	v_div_scale_f32 v38, vcc, 1.0, v26, 1.0
	v_mul_f32_e32 v39, v38, v33
	v_fma_f32 v40, -v27, v39, v38
	v_fmac_f32_e32 v39, v40, v33
	v_fma_f32 v27, -v27, v39, v38
	v_div_fmas_f32 v27, v27, v33, v39
	v_div_fixup_f32 v26, v27, v26, 1.0
	v_lshlrev_b32_e32 v38, 16, v34
	v_and_b32_e32 v39, 0xffff0000, v34
	v_pk_fma_f32 v[38:39], v[26:27], v[14:15], v[38:39] op_sel_hi:[0,1,1] neg_lo:[0,0,1] neg_hi:[0,0,1]
	v_cvt_pk_bf16_f32 v34, v38, v39
	v_lshlrev_b32_e32 v38, 16, v35
	v_and_b32_e32 v39, 0xffff0000, v35
	v_pk_fma_f32 v[38:39], v[26:27], v[12:13], v[38:39] op_sel_hi:[0,1,1] neg_lo:[0,0,1] neg_hi:[0,0,1]
	v_cvt_pk_bf16_f32 v35, v38, v39
	v_lshlrev_b32_e32 v38, 16, v36
	v_and_b32_e32 v39, 0xffff0000, v36
	v_pk_fma_f32 v[38:39], v[26:27], v[10:11], v[38:39] op_sel_hi:[0,1,1] neg_lo:[0,0,1] neg_hi:[0,0,1]
	v_cvt_pk_bf16_f32 v36, v38, v39
	v_lshlrev_b32_e32 v38, 16, v37
	v_and_b32_e32 v39, 0xffff0000, v37
	v_pk_fma_f32 v[26:27], v[26:27], v[8:9], v[38:39] op_sel_hi:[0,1,1] neg_lo:[0,0,1] neg_hi:[0,0,1]
	v_cvt_pk_bf16_f32 v37, v26, v27
	v_mad_u64_u32 v[26:27], s[26:27], v31, s48, v[24:25]
	ds_write_b128 v26, v[34:37]
	s_waitcnt lgkmcnt(11)
	v_mov_b32_e32 v34, v102
	v_mov_b32_e32 v35, v103
	v_mov_b32_e32 v36, v104
	v_mov_b32_e32 v37, v105
	ds_read_u16 v75, v138 offset:59664
	ds_read_b128 v[114:117], v30 offset:512
	ds_read_u16 v76, v138 offset:51216
	s_waitcnt lgkmcnt(10)
	v_mov_b32_e32 v38, v106
	v_mov_b32_e32 v39, v107
	v_mov_b32_e32 v40, v108
	v_mov_b32_e32 v41, v109
	ds_read_u16 v77, v138 offset:60192
	ds_read_u16 v78, v138 offset:60720
	ds_read_b128 v[118:121], v97 offset:512
	ds_read_u16 v79, v138 offset:34352
	v_or_b32_e32 v27, 1, v31
	v_add_u32_e32 v44, s47, v27
	v_or_b32_e32 v29, 3, v29
	v_lshlrev_b32_e32 v42, 16, v34
	v_lshlrev_b32_e32 v32, 16, v38
	v_and_b32_e32 v33, 0xffff0000, v38
	v_and_b32_e32 v43, 0xffff0000, v34
	v_pk_add_f32 v[32:33], v[32:33], v[42:43] neg_lo:[0,1] neg_hi:[0,1]
	v_lshlrev_b32_e32 v34, 16, v35
	v_pk_add_f32 v[32:33], v[14:15], v[32:33]
	v_lshlrev_b32_e32 v14, 16, v39
	v_and_b32_e32 v15, 0xffff0000, v39
	v_and_b32_e32 v35, 0xffff0000, v35
	v_pk_add_f32 v[14:15], v[14:15], v[34:35] neg_lo:[0,1] neg_hi:[0,1]
	s_and_b32 s23, s45, 0xffffff80
	v_pk_add_f32 v[34:35], v[12:13], v[14:15]
	v_lshlrev_b32_e32 v12, 16, v40
	v_and_b32_e32 v13, 0xffff0000, v40
	v_lshlrev_b32_e32 v14, 16, v36
	v_and_b32_e32 v15, 0xffff0000, v36
	v_pk_add_f32 v[12:13], v[12:13], v[14:15] neg_lo:[0,1] neg_hi:[0,1]
	v_mul_u32_u24_e32 v56, 0x840, v48
	v_pk_add_f32 v[38:39], v[10:11], v[12:13]
	v_lshlrev_b32_e32 v10, 16, v41
	v_and_b32_e32 v11, 0xffff0000, v41
	v_lshlrev_b32_e32 v12, 16, v37
	v_and_b32_e32 v13, 0xffff0000, v37
	v_pk_add_f32 v[10:11], v[10:11], v[12:13] neg_lo:[0,1] neg_hi:[0,1]
	s_add_i32 s23, s23, 0
	v_pk_add_f32 v[36:37], v[8:9], v[10:11]
	v_sub_u32_e32 v8, v44, v25
	v_max_i32_e32 v12, 0, v8
	v_add_u32_e32 v8, v44, v25
	v_min_i32_e32 v13, s46, v8
	v_sub_u32_e32 v12, v13, v12
	v_cvt_f32_i32_e32 v12, v12
	v_lshlrev_b32_e32 v8, 9, v27
	v_add3_u32 v8, s49, v8, v28
	s_waitcnt lgkmcnt(10)
	v_mov_b32_e32 v8, v110
	v_mov_b32_e32 v9, v111
	v_mov_b32_e32 v10, v112
	v_mov_b32_e32 v11, v113
	ds_read_u16 v80, v138 offset:34880
	ds_read_u16 v81, v138 offset:42272
	ds_read_b128 v[122:125], v96 offset:1024
	ds_read_u16 v82, v138 offset:51744
	v_div_scale_f32 v13, s[26:27], v12, v12, 1.0
	v_rcp_f32_e32 v14, v13
	s_nop 0
	v_fma_f32 v15, -v13, v14, 1.0
	v_fmac_f32_e32 v14, v15, v14
	v_div_scale_f32 v15, vcc, 1.0, v12, 1.0
	v_mul_f32_e32 v27, v15, v14
	v_fma_f32 v40, -v13, v27, v15
	v_fmac_f32_e32 v27, v40, v14
	v_fma_f32 v13, -v13, v27, v15
	v_div_fmas_f32 v13, v13, v14, v27
	v_div_fixup_f32 v12, v13, v12, 1.0
	v_lshlrev_b32_e32 v14, 16, v8
	v_and_b32_e32 v15, 0xffff0000, v8
	v_pk_fma_f32 v[14:15], v[12:13], v[32:33], v[14:15] op_sel_hi:[0,1,1] neg_lo:[0,0,1] neg_hi:[0,0,1]
	v_cvt_pk_bf16_f32 v8, v14, v15
	v_lshlrev_b32_e32 v14, 16, v9
	v_and_b32_e32 v15, 0xffff0000, v9
	v_pk_fma_f32 v[14:15], v[12:13], v[34:35], v[14:15] op_sel_hi:[0,1,1] neg_lo:[0,0,1] neg_hi:[0,0,1]
	v_cvt_pk_bf16_f32 v9, v14, v15
	v_lshlrev_b32_e32 v14, 16, v10
	v_and_b32_e32 v15, 0xffff0000, v10
	v_pk_fma_f32 v[14:15], v[12:13], v[38:39], v[14:15] op_sel_hi:[0,1,1] neg_lo:[0,0,1] neg_hi:[0,0,1]
	v_cvt_pk_bf16_f32 v10, v14, v15
	v_lshlrev_b32_e32 v14, 16, v11
	v_and_b32_e32 v15, 0xffff0000, v11
	v_pk_fma_f32 v[12:13], v[12:13], v[36:37], v[14:15] op_sel_hi:[0,1,1] neg_lo:[0,0,1] neg_hi:[0,0,1]
	v_cvt_pk_bf16_f32 v11, v12, v13
	ds_write_b128 v26, v[8:11] offset:528
	s_waitcnt lgkmcnt(10)
	v_mov_b32_e32 v8, v114
	v_mov_b32_e32 v9, v115
	v_mov_b32_e32 v10, v116
	v_mov_b32_e32 v11, v117
	ds_read_u16 v83, v138 offset:35408
	ds_read_u16 v84, v138 offset:52272
	ds_read_b128 v[126:129], v97 offset:1024
	ds_read_u16 v85, v138 offset:42800
	s_waitcnt lgkmcnt(10)
	v_mov_b32_e32 v12, v118
	v_mov_b32_e32 v13, v119
	v_mov_b32_e32 v14, v120
	v_mov_b32_e32 v15, v121
	ds_read_u16 v86, v138 offset:43328
	ds_read_u16 v87, v138 offset:50720
	ds_read_b128 v[130:133], v30 offset:1024
	ds_read_u16 v88, v138 offset:43856
	v_or_b32_e32 v27, 2, v31
	v_add_u32_e32 v31, s47, v27
	v_lshlrev_b32_e32 v42, 16, v8
	v_lshlrev_b32_e32 v40, 16, v12
	v_and_b32_e32 v41, 0xffff0000, v12
	v_and_b32_e32 v43, 0xffff0000, v8
	v_lshlrev_b32_e32 v12, 16, v13
	v_and_b32_e32 v13, 0xffff0000, v13
	v_lshlrev_b32_e32 v8, 16, v9
	v_and_b32_e32 v9, 0xffff0000, v9
	v_pk_add_f32 v[8:9], v[12:13], v[8:9] neg_lo:[0,1] neg_hi:[0,1]
	v_lshlrev_b32_e32 v12, 16, v10
	v_pk_add_f32 v[34:35], v[34:35], v[8:9]
	v_lshlrev_b32_e32 v8, 16, v14
	v_and_b32_e32 v9, 0xffff0000, v14
	v_and_b32_e32 v13, 0xffff0000, v10
	v_pk_add_f32 v[8:9], v[8:9], v[12:13] neg_lo:[0,1] neg_hi:[0,1]
	v_lshlrev_b32_e32 v10, 16, v11
	v_pk_add_f32 v[38:39], v[38:39], v[8:9]
	v_lshlrev_b32_e32 v8, 16, v15
	v_and_b32_e32 v9, 0xffff0000, v15
	v_and_b32_e32 v11, 0xffff0000, v11
	v_pk_add_f32 v[8:9], v[8:9], v[10:11] neg_lo:[0,1] neg_hi:[0,1]
	v_pk_add_f32 v[40:41], v[40:41], v[42:43] neg_lo:[0,1] neg_hi:[0,1]
	v_pk_add_f32 v[36:37], v[36:37], v[8:9]
	v_sub_u32_e32 v8, v31, v25
	v_max_i32_e32 v12, 0, v8
	v_add_u32_e32 v8, v31, v25
	v_min_i32_e32 v13, s46, v8
	v_sub_u32_e32 v12, v13, v12
	v_cvt_f32_i32_e32 v12, v12
	v_lshlrev_b32_e32 v8, 9, v27
	v_add3_u32 v8, s49, v8, v28
	s_waitcnt lgkmcnt(10)
	v_mov_b32_e32 v8, v122
	v_mov_b32_e32 v9, v123
	v_mov_b32_e32 v10, v124
	v_mov_b32_e32 v11, v125
	ds_read_u16 v89, v138 offset:51248
	ds_read_u16 v90, v138 offset:59168
	ds_read_b128 v[134:137], v96 offset:1536
	ds_read_u16 v91, v138 offset:51776
	v_div_scale_f32 v13, s[26:27], v12, v12, 1.0
	v_rcp_f32_e32 v14, v13
	v_pk_add_f32 v[32:33], v[32:33], v[40:41]
	v_fma_f32 v15, -v13, v14, 1.0
	v_fmac_f32_e32 v14, v15, v14
	v_div_scale_f32 v15, vcc, 1.0, v12, 1.0
	v_mul_f32_e32 v27, v15, v14
	v_fma_f32 v31, -v13, v27, v15
	v_fmac_f32_e32 v27, v31, v14
	v_fma_f32 v13, -v13, v27, v15
	v_div_fmas_f32 v13, v13, v14, v27
	v_div_fixup_f32 v12, v13, v12, 1.0
	v_lshlrev_b32_e32 v14, 16, v8
	v_and_b32_e32 v15, 0xffff0000, v8
	v_pk_fma_f32 v[14:15], v[12:13], v[32:33], v[14:15] op_sel_hi:[0,1,1] neg_lo:[0,0,1] neg_hi:[0,0,1]
	v_cvt_pk_bf16_f32 v8, v14, v15
	v_lshlrev_b32_e32 v14, 16, v9
	v_and_b32_e32 v15, 0xffff0000, v9
	v_pk_fma_f32 v[14:15], v[12:13], v[34:35], v[14:15] op_sel_hi:[0,1,1] neg_lo:[0,0,1] neg_hi:[0,0,1]
	v_cvt_pk_bf16_f32 v9, v14, v15
	v_lshlrev_b32_e32 v14, 16, v10
	v_and_b32_e32 v15, 0xffff0000, v10
	v_pk_fma_f32 v[14:15], v[12:13], v[38:39], v[14:15] op_sel_hi:[0,1,1] neg_lo:[0,0,1] neg_hi:[0,0,1]
	v_cvt_pk_bf16_f32 v10, v14, v15
	v_lshlrev_b32_e32 v14, 16, v11
	v_and_b32_e32 v15, 0xffff0000, v11
	v_pk_fma_f32 v[12:13], v[12:13], v[36:37], v[14:15] op_sel_hi:[0,1,1] neg_lo:[0,0,1] neg_hi:[0,0,1]
	v_cvt_pk_bf16_f32 v11, v12, v13
	ds_write_b128 v26, v[8:11] offset:1056
	s_waitcnt lgkmcnt(10)
	v_mov_b32_e32 v8, v126
	v_mov_b32_e32 v9, v127
	v_mov_b32_e32 v10, v128
	v_mov_b32_e32 v11, v129
	ds_read_u16 v92, v138 offset:59696
	ds_read_u16 v93, v138 offset:52304
	ds_read_u16 v94, v138 offset:60224
	ds_read_u16 v95, v138 offset:60752
	s_waitcnt lgkmcnt(10)
	v_mov_b32_e32 v12, v130
	v_mov_b32_e32 v13, v131
	v_mov_b32_e32 v14, v132
	v_mov_b32_e32 v15, v133
	v_lshlrev_b32_e32 v26, 16, v11
	v_and_b32_e32 v27, 0xffff0000, v11
	v_lshlrev_b32_e32 v30, 16, v15
	v_and_b32_e32 v31, 0xffff0000, v15
	v_pk_add_f32 v[26:27], v[26:27], v[30:31] neg_lo:[0,1] neg_hi:[0,1]
	v_lshlrev_b32_e32 v30, 16, v10
	v_and_b32_e32 v31, 0xffff0000, v10
	v_lshlrev_b32_e32 v10, 16, v14
	v_and_b32_e32 v11, 0xffff0000, v14
	v_pk_add_f32 v[10:11], v[30:31], v[10:11] neg_lo:[0,1] neg_hi:[0,1]
	v_lshlrev_b32_e32 v30, 16, v13
	v_pk_add_f32 v[14:15], v[38:39], v[10:11]
	v_lshlrev_b32_e32 v10, 16, v9
	v_and_b32_e32 v11, 0xffff0000, v9
	v_and_b32_e32 v31, 0xffff0000, v13
	v_pk_add_f32 v[10:11], v[10:11], v[30:31] neg_lo:[0,1] neg_hi:[0,1]
	v_and_b32_e32 v9, 0xffff0000, v12
	v_pk_add_f32 v[30:31], v[34:35], v[10:11]
	v_lshlrev_b32_e32 v10, 16, v8
	v_and_b32_e32 v11, 0xffff0000, v8
	v_lshlrev_b32_e32 v8, 16, v12
	v_pk_add_f32 v[8:9], v[10:11], v[8:9] neg_lo:[0,1] neg_hi:[0,1]
	v_pk_add_f32 v[26:27], v[36:37], v[26:27]
	v_pk_add_f32 v[12:13], v[32:33], v[8:9]
	v_add_u32_e32 v8, s47, v29
	v_sub_u32_e32 v9, v8, v25
	v_add_u32_e32 v8, v8, v25
	v_max_i32_e32 v32, 0, v9
	v_min_i32_e32 v25, s46, v8
	v_sub_u32_e32 v25, v25, v32
	v_cvt_f32_i32_e32 v25, v25
	v_lshlrev_b32_e32 v8, 9, v29
	v_add3_u32 v8, s49, v8, v28
	s_waitcnt lgkmcnt(6)
	v_mov_b32_e32 v8, v134
	v_mov_b32_e32 v9, v135
	v_mov_b32_e32 v10, v136
	v_mov_b32_e32 v11, v137
	v_div_scale_f32 v28, s[26:27], v25, v25, 1.0
	v_rcp_f32_e32 v32, v28
	s_nop 0
	v_fma_f32 v33, -v28, v32, 1.0
	v_fmac_f32_e32 v32, v33, v32
	v_div_scale_f32 v33, vcc, 1.0, v25, 1.0
	v_mul_f32_e32 v34, v33, v32
	v_fma_f32 v35, -v28, v34, v33
	v_fmac_f32_e32 v34, v35, v32
	v_fma_f32 v28, -v28, v34, v33
	v_div_fmas_f32 v28, v28, v32, v34
	v_div_fixup_f32 v28, v28, v25, 1.0
	v_lshlrev_b32_e32 v32, 16, v8
	v_and_b32_e32 v33, 0xffff0000, v8
	v_pk_fma_f32 v[12:13], v[28:29], v[12:13], v[32:33] op_sel_hi:[0,1,1] neg_lo:[0,0,1] neg_hi:[0,0,1]
	v_cvt_pk_bf16_f32 v8, v12, v13
	v_lshlrev_b32_e32 v12, 16, v9
	v_and_b32_e32 v13, 0xffff0000, v9
	v_pk_fma_f32 v[12:13], v[28:29], v[30:31], v[12:13] op_sel_hi:[0,1,1] neg_lo:[0,0,1] neg_hi:[0,0,1]
	v_cvt_pk_bf16_f32 v9, v12, v13
	v_lshlrev_b32_e32 v12, 16, v10
	v_and_b32_e32 v13, 0xffff0000, v10
	v_pk_fma_f32 v[12:13], v[28:29], v[14:15], v[12:13] op_sel_hi:[0,1,1] neg_lo:[0,0,1] neg_hi:[0,0,1]
	v_cvt_pk_bf16_f32 v10, v12, v13
	v_lshlrev_b32_e32 v12, 16, v11
	v_and_b32_e32 v13, 0xffff0000, v11
	v_pk_fma_f32 v[12:13], v[28:29], v[26:27], v[12:13] op_sel_hi:[0,1,1] neg_lo:[0,0,1] neg_hi:[0,0,1]
	v_cvt_pk_bf16_f32 v11, v12, v13
	v_mad_u64_u32 v[12:13], s[26:27], v29, s48, v[24:25]
	ds_write_b128 v12, v[8:11]
	v_mul_u32_u24_e32 v8, 0x210, v49
	v_or_b32_e32 v49, s43, v49
	v_or_b32_e32 v51, s42, v49
	v_add_u32_e32 v48, s24, v51
	v_ashrrev_i32_e32 v49, 31, v48
	v_add3_u32 v12, s23, v148, v8
	v_lshl_add_u64 v[48:49], v[48:49], 2, s[88:89]
	s_waitcnt lgkmcnt(0)
	s_barrier
	ds_read_b128 v[40:43], v12
	ds_read_b128 v[44:47], v12 offset:64
	ds_read_b128 v[32:35], v12 offset:8448
	ds_read_b128 v[36:39], v12 offset:8512
	ds_read_b128 v[24:27], v12 offset:16896
	ds_read_b128 v[28:31], v12 offset:16960
	ds_read_b128 v[8:11], v12 offset:25344
	ds_read_b128 v[12:15], v12 offset:25408
	v_lshlrev_b32_e32 v51, 1, v51
	v_add3_u32 v51, 0, v51, v56
	s_waitcnt vmcnt(4) lgkmcnt(7)
	v_mfma_f32_16x16x32_bf16 v[52:55], v[40:43], v[16:19], 0
	v_readlane_b32 s26, v255, 11
	v_readlane_b32 s27, v255, 12
	s_waitcnt lgkmcnt(0)
	v_lshlrev_b32_e32 v56, 16, v64
	v_mul_f32_e32 v58, 0xbfb8aa3b, v56
	v_exp_f32_e32 v58, v58
	s_waitcnt vmcnt(3)
	v_mfma_f32_16x16x32_bf16 v[52:55], v[44:47], v[20:23], v[52:55]
	v_add_f32_e32 v58, 1.0, v58
	v_rcp_f32_e32 v58, v58
	s_nop 0
	v_mul_f32_e32 v56, v58, v56
	s_waitcnt vmcnt(0)
	s_nop 2
	v_mul_f32_e32 v52, v57, v52
	v_mul_f32_e32 v52, v52, v56
	v_cvt_pk_bf16_f32 v52, v52, s0
	ds_write_b16 v51, v52 offset:33792
	s_nop 0
	v_mul_f32_e32 v53, v57, v53
	v_lshlrev_b32_e32 v52, 16, v65
	v_mul_f32_e32 v56, 0xbfb8aa3b, v52
	v_exp_f32_e32 v56, v56
	s_nop 0
	v_add_f32_e32 v56, 1.0, v56
	v_rcp_f32_e32 v56, v56
	s_nop 0
	v_mul_f32_e32 v52, v56, v52
	v_mul_f32_e32 v52, v53, v52
	v_cvt_pk_bf16_f32 v52, v52, s0
	ds_write_b16 v51, v52 offset:34320
	v_mul_f32_e32 v53, v57, v54
	v_lshlrev_b32_e32 v52, 16, v66
	v_mul_f32_e32 v54, 0xbfb8aa3b, v52
	v_exp_f32_e32 v54, v54
	s_nop 0
	v_lshlrev_b32_e32 v56, 16, v67
	v_mul_f32_e32 v58, 0xbfb8aa3b, v56
	v_exp_f32_e32 v58, v58
	v_add_f32_e32 v54, 1.0, v54
	v_rcp_f32_e32 v54, v54
	v_add_f32_e32 v58, 1.0, v58
	v_rcp_f32_e32 v58, v58
	v_mul_f32_e32 v52, v54, v52
	v_mul_f32_e32 v52, v53, v52
	v_cvt_pk_bf16_f32 v52, v52, s0
	ds_write_b16 v51, v52 offset:34848
	v_mul_f32_e32 v53, v57, v55
	v_mul_f32_e32 v56, v58, v56
	v_lshlrev_b32_e32 v52, 16, v68
	v_mul_f32_e32 v54, 0xbfb8aa3b, v52
	v_exp_f32_e32 v54, v54
	s_nop 0
	v_add_f32_e32 v54, 1.0, v54
	v_rcp_f32_e32 v54, v54
	s_nop 0
	v_mul_f32_e32 v52, v54, v52
	v_mul_f32_e32 v52, v53, v52
	v_cvt_pk_bf16_f32 v52, v52, s0
	ds_write_b16 v51, v52 offset:35376
	v_mfma_f32_16x16x32_bf16 v[52:55], v[32:35], v[16:19], 0
	v_mfma_f32_16x16x32_bf16 v[52:55], v[36:39], v[20:23], v[52:55]
	s_nop 7
	v_mul_f32_e32 v52, v57, v52
	v_mul_f32_e32 v52, v52, v56
	v_cvt_pk_bf16_f32 v52, v52, s0
	ds_write_b16 v51, v52 offset:42240
	s_nop 0
	v_mul_f32_e32 v53, v57, v53
	s_nop 0
	v_lshlrev_b32_e32 v52, 16, v69
	v_mul_f32_e32 v56, 0xbfb8aa3b, v52
	v_exp_f32_e32 v56, v56
	s_nop 0
	v_add_f32_e32 v56, 1.0, v56
	v_rcp_f32_e32 v56, v56
	s_nop 0
	v_mul_f32_e32 v52, v56, v52
	v_mul_f32_e32 v52, v53, v52
	v_cvt_pk_bf16_f32 v52, v52, s0
	ds_write_b16 v51, v52 offset:42768
	v_mul_f32_e32 v53, v57, v54
	v_lshlrev_b32_e32 v52, 16, v70
	v_mul_f32_e32 v54, 0xbfb8aa3b, v52
	v_exp_f32_e32 v54, v54
	s_nop 0
	v_add_f32_e32 v54, 1.0, v54
	v_rcp_f32_e32 v54, v54
	s_nop 0
	v_mul_f32_e32 v52, v54, v52
	v_mul_f32_e32 v52, v53, v52
	v_cvt_pk_bf16_f32 v52, v52, s0
	ds_write_b16 v51, v52 offset:43296
	v_mul_f32_e32 v53, v57, v55
	v_lshlrev_b32_e32 v52, 16, v72
	v_mul_f32_e32 v54, 0xbfb8aa3b, v52
	v_exp_f32_e32 v54, v54
	s_nop 0
	v_add_f32_e32 v54, 1.0, v54
	v_rcp_f32_e32 v54, v54
	s_nop 0
	v_mul_f32_e32 v52, v54, v52
	v_mul_f32_e32 v52, v53, v52
	v_cvt_pk_bf16_f32 v52, v52, s0
	ds_write_b16 v51, v52 offset:43824
	v_mfma_f32_16x16x32_bf16 v[52:55], v[24:27], v[16:19], 0
	v_mfma_f32_16x16x32_bf16 v[16:19], v[8:11], v[16:19], 0
	v_mfma_f32_16x16x32_bf16 v[52:55], v[28:31], v[20:23], v[52:55]
	v_mfma_f32_16x16x32_bf16 v[16:19], v[12:15], v[20:23], v[16:19]
	s_nop 0
	s_nop 5
	v_mul_f32_e32 v52, v57, v52
	v_mul_f32_e32 v53, v57, v53
	s_nop 0
	v_lshlrev_b32_e32 v20, 16, v73
	v_mul_f32_e32 v21, 0xbfb8aa3b, v20
	v_exp_f32_e32 v21, v21
	v_mul_f32_e32 v16, v57, v16
	v_mul_f32_e32 v17, v57, v17
	v_add_f32_e32 v21, 1.0, v21
	v_rcp_f32_e32 v21, v21
	s_nop 0
	v_mul_f32_e32 v20, v21, v20
	v_lshlrev_b32_e32 v56, 16, v71
	v_mul_f32_e32 v58, 0xbfb8aa3b, v56
	v_exp_f32_e32 v58, v58
	v_mul_f32_e32 v16, v16, v20
	v_cvt_pk_bf16_f32 v16, v16, s0
	ds_write_b16 v51, v16 offset:59136
	v_add_f32_e32 v58, 1.0, v58
	v_rcp_f32_e32 v58, v58
	s_nop 0
	v_lshlrev_b32_e32 v21, 16, v74
	v_mul_f32_e32 v22, 0xbfb8aa3b, v21
	v_mul_f32_e32 v56, v58, v56
	v_mul_f32_e32 v52, v52, v56
	v_cvt_pk_bf16_f32 v52, v52, s0
	ds_write_b16 v51, v52 offset:50688
	v_lshlrev_b32_e32 v16, 16, v75
	v_mul_f32_e32 v20, 0xbfb8aa3b, v16
	v_exp_f32_e32 v20, v20
	v_exp_f32_e32 v22, v22
	v_add_f32_e32 v20, 1.0, v20
	v_rcp_f32_e32 v20, v20
	v_add_f32_e32 v22, 1.0, v22
	v_rcp_f32_e32 v22, v22
	v_mul_f32_e32 v16, v20, v16
	v_mov_b32_e32 v20, v249
	v_mul_f32_e32 v16, v17, v16
	v_cvt_pk_bf16_f32 v16, v16, s0
	ds_write_b16 v51, v16 offset:59664
	v_mul_f32_e32 v17, v57, v18
	v_mul_f32_e32 v21, v22, v21
	v_lshlrev_b32_e32 v16, 16, v77
	v_mul_f32_e32 v18, 0xbfb8aa3b, v16
	v_exp_f32_e32 v18, v18
	s_nop 0
	v_add_f32_e32 v18, 1.0, v18
	v_rcp_f32_e32 v18, v18
	s_nop 0
	v_mul_f32_e32 v16, v18, v16
	v_mul_f32_e32 v16, v17, v16
	v_cvt_pk_bf16_f32 v16, v16, s0
	ds_write_b16 v51, v16 offset:60192
	v_mul_f32_e32 v17, v57, v19
	v_lshlrev_b32_e32 v16, 16, v78
	v_mul_f32_e32 v18, 0xbfb8aa3b, v16
	v_exp_f32_e32 v18, v18
	s_nop 0
	v_add_f32_e32 v18, 1.0, v18
	v_rcp_f32_e32 v18, v18
	s_nop 0
	v_mul_f32_e32 v16, v18, v16
	v_mul_f32_e32 v16, v17, v16
	v_cvt_pk_bf16_f32 v16, v16, s0
	ds_write_b16 v51, v16 offset:60720
	v_mfma_f32_16x16x32_bf16 v[16:19], v[40:43], v[0:3], 0
	v_mfma_f32_16x16x32_bf16 v[16:19], v[44:47], v[4:7], v[16:19]
	s_waitcnt vmcnt(0)
	s_nop 6
	v_mul_f32_e32 v16, v20, v16
	v_mul_f32_e32 v16, v16, v21
	v_cvt_pk_bf16_f32 v16, v16, s0
	ds_write_b16 v51, v16 offset:33824
	s_nop 0
	v_mul_f32_e32 v17, v20, v17
	v_lshlrev_b32_e32 v52, 16, v76
	v_mul_f32_e32 v56, 0xbfb8aa3b, v52
	v_exp_f32_e32 v56, v56
	s_nop 0
	v_lshlrev_b32_e32 v16, 16, v79
	v_mul_f32_e32 v21, 0xbfb8aa3b, v16
	v_exp_f32_e32 v21, v21
	v_add_f32_e32 v56, 1.0, v56
	v_rcp_f32_e32 v56, v56
	v_add_f32_e32 v21, 1.0, v21
	v_rcp_f32_e32 v21, v21
	v_mul_f32_e32 v52, v56, v52
	v_mul_f32_e32 v52, v53, v52
	v_cvt_pk_bf16_f32 v52, v52, s0
	v_mul_f32_e32 v16, v21, v16
	v_mul_f32_e32 v16, v17, v16
	v_cvt_pk_bf16_f32 v16, v16, s0
	ds_write_b16 v51, v16 offset:34352
	v_mul_f32_e32 v17, v20, v18
	ds_write_b16 v51, v52 offset:51216
	v_lshlrev_b32_e32 v16, 16, v80
	v_mul_f32_e32 v18, 0xbfb8aa3b, v16
	v_exp_f32_e32 v18, v18
	s_nop 0
	v_lshlrev_b32_e32 v21, 16, v81
	v_mul_f32_e32 v53, v57, v54
	v_mul_f32_e32 v22, 0xbfb8aa3b, v21
	v_add_f32_e32 v18, 1.0, v18
	v_rcp_f32_e32 v18, v18
	v_exp_f32_e32 v22, v22
	v_mul_f32_e32 v16, v18, v16
	v_mul_f32_e32 v16, v17, v16
	v_cvt_pk_bf16_f32 v16, v16, s0
	ds_write_b16 v51, v16 offset:34880
	v_lshlrev_b32_e32 v52, 16, v82
	v_mul_f32_e32 v17, v20, v19
	v_mul_f32_e32 v54, 0xbfb8aa3b, v52
	v_exp_f32_e32 v54, v54
	s_nop 0
	v_lshlrev_b32_e32 v16, 16, v83
	v_mul_f32_e32 v18, 0xbfb8aa3b, v16
	v_exp_f32_e32 v18, v18
	v_add_f32_e32 v54, 1.0, v54
	v_add_f32_e32 v22, 1.0, v22
	v_rcp_f32_e32 v54, v54
	v_add_f32_e32 v18, 1.0, v18
	v_rcp_f32_e32 v18, v18
	v_rcp_f32_e32 v22, v22
	v_mul_f32_e32 v52, v54, v52
	v_mul_f32_e32 v52, v53, v52
	v_mul_f32_e32 v16, v18, v16
	v_mul_f32_e32 v16, v17, v16
	v_cvt_pk_bf16_f32 v16, v16, s0
	ds_write_b16 v51, v16 offset:35408
	v_mfma_f32_16x16x32_bf16 v[16:19], v[32:35], v[0:3], 0
	v_mul_f32_e32 v21, v22, v21
	v_cvt_pk_bf16_f32 v52, v52, s0
	ds_write_b16 v51, v52 offset:51744
	v_mfma_f32_16x16x32_bf16 v[16:19], v[36:39], v[4:7], v[16:19]
	s_nop 0
	v_mul_f32_e32 v53, v57, v55
	s_nop 5
	v_mul_f32_e32 v16, v20, v16
	v_mul_f32_e32 v16, v16, v21
	v_cvt_pk_bf16_f32 v16, v16, s0
	ds_write_b16 v51, v16 offset:42272
	s_nop 0
	v_mul_f32_e32 v17, v20, v17
	s_nop 0
	v_lshlrev_b32_e32 v52, 16, v84
	v_mul_f32_e32 v54, 0xbfb8aa3b, v52
	v_exp_f32_e32 v54, v54
	s_nop 0
	v_lshlrev_b32_e32 v16, 16, v85
	v_mul_f32_e32 v21, 0xbfb8aa3b, v16
	v_exp_f32_e32 v21, v21
	v_add_f32_e32 v54, 1.0, v54
	v_rcp_f32_e32 v54, v54
	v_add_f32_e32 v21, 1.0, v21
	v_rcp_f32_e32 v21, v21
	v_mul_f32_e32 v52, v54, v52
	v_mul_f32_e32 v52, v53, v52
	v_cvt_pk_bf16_f32 v52, v52, s0
	v_mul_f32_e32 v16, v21, v16
	v_mul_f32_e32 v16, v17, v16
	v_cvt_pk_bf16_f32 v16, v16, s0
	ds_write_b16 v51, v16 offset:42800
	v_mul_f32_e32 v17, v20, v18
	ds_write_b16 v51, v52 offset:52272
	v_lshlrev_b32_e32 v16, 16, v86
	v_mul_f32_e32 v18, 0xbfb8aa3b, v16
	v_exp_f32_e32 v18, v18
	s_nop 0
	v_lshlrev_b32_e32 v21, 16, v87
	v_mul_f32_e32 v22, 0xbfb8aa3b, v21
	v_exp_f32_e32 v22, v22
	v_add_f32_e32 v18, 1.0, v18
	v_rcp_f32_e32 v18, v18
	v_add_f32_e32 v22, 1.0, v22
	v_rcp_f32_e32 v22, v22
	v_mul_f32_e32 v16, v18, v16
	v_mul_f32_e32 v16, v17, v16
	v_cvt_pk_bf16_f32 v16, v16, s0
	ds_write_b16 v51, v16 offset:43328
	v_mul_f32_e32 v17, v20, v19
	v_mul_f32_e32 v21, v22, v21
	v_lshlrev_b32_e32 v16, 16, v88
	v_mul_f32_e32 v18, 0xbfb8aa3b, v16
	v_exp_f32_e32 v18, v18
	s_nop 0
	v_add_f32_e32 v18, 1.0, v18
	v_rcp_f32_e32 v18, v18
	s_nop 0
	v_mul_f32_e32 v16, v18, v16
	v_mul_f32_e32 v16, v17, v16
	v_cvt_pk_bf16_f32 v16, v16, s0
	ds_write_b16 v51, v16 offset:43856
	v_mfma_f32_16x16x32_bf16 v[16:19], v[24:27], v[0:3], 0
	v_mfma_f32_16x16x32_bf16 v[16:19], v[28:31], v[4:7], v[16:19]
	v_mfma_f32_16x16x32_bf16 v[0:3], v[8:11], v[0:3], 0
	v_mfma_f32_16x16x32_bf16 v[0:3], v[12:15], v[4:7], v[0:3]
	s_nop 5
	v_mul_f32_e32 v16, v20, v16
	v_mul_f32_e32 v16, v16, v21
	v_cvt_pk_bf16_f32 v16, v16, s0
	ds_write_b16 v51, v16 offset:50720
	s_nop 0
	s_nop 0
	v_mul_f32_e32 v17, v20, v17
	v_mul_f32_e32 v0, v20, v0
	v_mul_f32_e32 v1, v20, v1
	s_nop 0
	v_lshlrev_b32_e32 v16, 16, v89
	v_lshlrev_b32_e32 v4, 16, v90
	v_mul_f32_e32 v21, 0xbfb8aa3b, v16
	v_mul_f32_e32 v5, 0xbfb8aa3b, v4
	v_exp_f32_e32 v21, v21
	v_exp_f32_e32 v5, v5
	v_add_f32_e32 v21, 1.0, v21
	v_add_f32_e32 v5, 1.0, v5
	v_rcp_f32_e32 v21, v21
	v_rcp_f32_e32 v5, v5
	v_mul_f32_e32 v16, v21, v16
	v_mul_f32_e32 v4, v5, v4
	v_mul_f32_e32 v16, v17, v16
	v_mul_f32_e32 v0, v0, v4
	v_cvt_pk_bf16_f32 v16, v16, s0
	v_cvt_pk_bf16_f32 v0, v0, s0
	ds_write_b16 v51, v16 offset:51248
	ds_write_b16 v51, v0 offset:59168
	v_mul_f32_e32 v17, v20, v18
	v_lshlrev_b32_e32 v16, 16, v91
	v_mul_f32_e32 v18, 0xbfb8aa3b, v16
	v_lshlrev_b32_e32 v0, 16, v92
	v_mul_f32_e32 v4, 0xbfb8aa3b, v0
	v_exp_f32_e32 v18, v18
	v_exp_f32_e32 v4, v4
	v_add_f32_e32 v18, 1.0, v18
	v_add_f32_e32 v4, 1.0, v4
	v_rcp_f32_e32 v18, v18
	v_rcp_f32_e32 v4, v4
	v_mul_f32_e32 v16, v18, v16
	v_mul_f32_e32 v0, v4, v0
	v_mul_f32_e32 v16, v17, v16
	v_mul_f32_e32 v0, v1, v0
	v_cvt_pk_bf16_f32 v16, v16, s0
	v_cvt_pk_bf16_f32 v0, v0, s0
	ds_write_b16 v51, v16 offset:51776
	ds_write_b16 v51, v0 offset:59696
	v_mul_f32_e32 v1, v20, v2
	v_mul_f32_e32 v17, v20, v19
	v_lshlrev_b32_e32 v16, 16, v93
	v_mul_f32_e32 v18, 0xbfb8aa3b, v16
	v_lshlrev_b32_e32 v0, 16, v94
	v_mul_f32_e32 v2, 0xbfb8aa3b, v0
	v_exp_f32_e32 v2, v2
	v_exp_f32_e32 v18, v18
	v_add_f32_e32 v2, 1.0, v2
	v_rcp_f32_e32 v2, v2
	v_add_f32_e32 v18, 1.0, v18
	v_rcp_f32_e32 v18, v18
	v_mul_f32_e32 v0, v2, v0
	v_mul_f32_e32 v0, v1, v0
	v_cvt_pk_bf16_f32 v0, v0, s0
	ds_write_b16 v51, v0 offset:60224
	v_mul_f32_e32 v1, v20, v3
	v_mul_f32_e32 v16, v18, v16
	v_mul_f32_e32 v16, v17, v16
	v_cvt_pk_bf16_f32 v16, v16, s0
	v_lshlrev_b32_e32 v0, 16, v95
	v_mul_f32_e32 v2, 0xbfb8aa3b, v0
	v_exp_f32_e32 v2, v2
	ds_write_b16 v51, v16 offset:52304
	v_add_f32_e32 v2, 1.0, v2
	v_rcp_f32_e32 v2, v2
	s_nop 0
	v_mul_f32_e32 v0, v2, v0
	v_mul_f32_e32 v0, v1, v0
	v_cvt_pk_bf16_f32 v0, v0, s0
	ds_write_b16 v51, v0 offset:60752
	v_ashrrev_i32_e32 v0, 31, v50
	v_lshrrev_b32_e32 v0, 27, v0
	v_add_u32_e32 v0, v50, v0
	v_ashrrev_i32_e32 v2, 5, v0
	v_and_b32_e32 v0, 0xffffffe0, v0
	v_sub_u32_e32 v3, v50, v0
	v_lshlrev_b32_e32 v0, 3, v3
	v_add_u32_e32 v6, s44, v2
	v_ashrrev_i32_e32 v1, 31, v0
	v_ashrrev_i32_e32 v7, 31, v6
	v_lshl_add_u64 v[4:5], v[0:1], 1, s[26:27]
	v_lshlrev_b64 v[0:1], 11, v[6:7]
	v_lshlrev_b32_e32 v3, 4, v3
	v_lshl_add_u64 v[8:9], v[4:5], 0, v[0:1]
	v_mul_lo_u32 v0, v2, s48
	v_add3_u32 v7, 0, v3, v0
	s_waitcnt lgkmcnt(0)
	s_barrier
	ds_read_b128 v[0:3], v7 offset:33792
	ds_read_b128 v[16:19], v7 offset:42240
	ds_read_b128 v[20:23], v7 offset:50688
	ds_read_b128 v[24:27], v7 offset:59136
	s_waitcnt lgkmcnt(3)
	global_store_dwordx4 v[8:9], v[0:3], off sc1
	s_nop 1
	v_add_u32_e32 v0, 16, v6
	v_ashrrev_i32_e32 v1, 31, v0
	v_lshlrev_b64 v[0:1], 11, v[0:1]
	v_lshl_add_u64 v[8:9], v[4:5], 0, v[0:1]
	s_waitcnt lgkmcnt(2)
	global_store_dwordx4 v[8:9], v[16:19], off sc1
	s_nop 1
	v_add_u32_e32 v0, 32, v6
	v_ashrrev_i32_e32 v1, 31, v0
	v_lshlrev_b64 v[0:1], 11, v[0:1]
	v_lshl_add_u64 v[8:9], v[4:5], 0, v[0:1]
	s_waitcnt lgkmcnt(1)
	global_store_dwordx4 v[8:9], v[20:23], off sc1
	s_nop 1
	v_add_u32_e32 v0, 48, v6
	v_ashrrev_i32_e32 v1, 31, v0
	v_lshlrev_b64 v[0:1], 11, v[0:1]
	v_lshl_add_u64 v[4:5], v[4:5], 0, v[0:1]
	s_waitcnt lgkmcnt(0)
	global_store_dwordx4 v[4:5], v[24:27], off sc1
	s_nop 1
	v_mov_b32_e32 v0, v147
	s_barrier
	s_branch .LBB0_641
